# layer-0 W13 conversion also moved: done by the 208 WGs without a half unit in the in-proj last round (after trig tables); P1 skips W13 tiles in both layers
# speedup vs baseline: 1.0080x; 1.0009x over previous
; #define WT_LOAD() do { _Pragma("unroll") for (int i = 0; i < 16; ++i) rg[i] = sp ? sp[(size_t)(k0 + kq + i * 8) * ld] : 0.f; } while (0)
; __device__ __forceinline__ void phase_weights(int wv, const Params& p, int l, LAS unsigned char* lds, int first, int stride) {
;     ...
;     if (ti < 1536) { WT_DECODE(ti); WT_LOAD(); }
;     while (ti < 1536) {
;         bf16_t* cdst = dst + (size_t)n0 * K + k0; const int cK = K;
;         __syncthreads();
; #pragma unroll
;         for (int i = 0; i < 16; ++i) tile[(kq + i * 8) * 65 + nl] = rg[i];
;         ti += stride;
;         if (ti < 1536) { WT_DECODE(ti); WT_LOAD(); }
.LBB0_232:
	s_add_i32 s46, s46, s1
	s_cmpk_lg_u32 s44, 0x100
	s_cbranch_scc1 .Lws_done

; __device__ __forceinline__ unsigned pk_bf16(float lo, float hi) { unsigned r; asm volatile("v_cvt_pk_bf16_f32 %0, %1, %2" : "=v"(r) : "v"(lo), "v"(hi)); return r; }
; #define WT_LOAD() do { _Pragma("unroll") for (int i = 0; i < 16; ++i) rg[i] = sp ? sp[(size_t)(k0 + kq + i * 8) * ld] : 0.f; } while (0)
; __device__ __forceinline__ void phase_weights(int wv, const Params& p, int l, LAS unsigned char* lds, int first, int stride) {
;     ...
;     if (ti < 1536) { WT_DECODE(ti); WT_LOAD(); }
;     while (ti < 1536) {
;         bf16_t* cdst = dst + (size_t)n0 * K + k0; const int cK = K;
;         __syncthreads();
; #pragma unroll
;         for (int i = 0; i < 16; ++i) tile[(kq + i * 8) * 65 + nl] = rg[i];
;         ti += stride;
;         if (ti < 1536) { WT_DECODE(ti); WT_LOAD(); }
;         __syncthreads();
;         { const int nn = tid >> 3, ks = tid & 7; float v[16];
; #pragma unroll
;             for (int j = 0; j < 16; ++j) v[j] = tile[(ks * 16 + j) * 65 + nn];
;             u32x4 w0, w1; w0.x = pk_bf16(v[0], v[1]); w0.y = pk_bf16(v[2], v[3]); w0.z = pk_bf16(v[4], v[5]); w0.w = pk_bf16(v[6], v[7]);
;             w1.x = pk_bf16(v[8], v[9]); w1.y = pk_bf16(v[10], v[11]); w1.z = pk_bf16(v[12], v[13]); w1.w = pk_bf16(v[14], v[15]);
;             bf16_t* o = cdst + (size_t)nn * cK + ks * 16; *(u32x4*)o = w0; *(u32x4*)(o + 8) = w1; }
.LBB0_534:
	s_cmpk_lt_u32 s96, 48
	s_cbranch_scc1 .Lew_end_a
	s_cmpk_lg_u32 s44, 0x100
	s_cbranch_scc1 .Lew_end_a
	v_readlane_b32 s24, v255, 22
	s_cmp_lg_u32 s24, 0
	s_cbranch_scc1 .Lew_end_a
	s_load_dwordx2 s[8:9], s[90:91], 0x88
	s_load_dwordx2 s[10:11], s[90:91], 0x90
	s_load_dwordx2 s[12:13], s[90:91], 0xa8
	v_readlane_b32 s24, v255, 7
	v_mbcnt_lo_u32_b32 v2, -1, 0
	v_mbcnt_hi_u32_b32 v2, -1, v2
	v_and_b32_e32 v3, 15, v2
	v_lshrrev_b32_e32 v6, 5, v2
	v_lshlrev_b32_e32 v7, 4, v3
	v_mul_u32_u24_e32 v8, 0x2c000, v6
	v_add_u32_e32 v12, v7, v8
	v_mov_b32_e32 v13, 0
	v_and_b32_e32 v8, 16, v2
	v_cmp_ne_u32_e32 vcc, 0, v8
	s_waitcnt lgkmcnt(0)
	v_mov_b32_e32 v4, s8
	v_mov_b32_e32 v5, s9
	v_mov_b32_e32 v8, s10
	v_mov_b32_e32 v9, s11
	s_nop 1
	v_cndmask_b32_e32 v4, v4, v8, vcc
	v_cndmask_b32_e32 v5, v5, v9, vcc
	v_lshl_add_u64 v[4:5], v[4:5], 0, v[12:13]
	v_and_b32_e32 v8, 1, v3
	v_lshlrev_b32_e32 v10, 7, v8
	v_bfe_u32 v8, v3, 1, 2
	v_lshl_add_u32 v10, v8, 2, v10
	v_lshrrev_b32_e32 v8, 3, v3
	v_lshl_add_u32 v10, v8, 5, v10
	v_bfe_u32 v8, v2, 4, 1
	v_lshl_add_u32 v10, v8, 4, v10
	v_add_u32_e32 v10, 2, v10
	v_lshlrev_b32_e32 v10, 11, v10
	v_lshl_add_u32 v10, v6, 5, v10
	s_add_u32 s12, s12, 0xb34c000
	s_addc_u32 s13, s13, 0
	s_lshr_b32 s24, s24, 6
	s_sub_i32 s3, s96, 48
	s_lshl_b32 s3, s3, 3
	s_add_i32 s3, s3, s24
.Lew_loop_a:
	s_cmpk_gt_u32 s3, 0x57f
	s_cbranch_scc1 .Lew_end_a
	s_lshr_b32 s6, s3, 5
	s_and_b32 s7, s3, 31
	s_lshr_b32 s14, s6, 1
	s_and_b32 s15, s6, 1
	s_lshl_b32 s26, s14, 9
	s_lshl_b32 s27, s15, 8
	s_add_i32 s26, s26, s27
	s_mul_i32 s27, s7, 0x58000
	s_add_i32 s28, s26, s27
	s_mov_b32 s29, 0
	v_lshl_add_u64 v[6:7], s[28:29], 0, v[4:5]
	global_load_dwordx4 v[20:23], v[6:7], off
	s_add_u32 s28, s28, 0x2c00
	v_lshl_add_u64 v[8:9], s[28:29], 0, v[4:5]
	global_load_dwordx4 v[24:27], v[8:9], off
	s_add_u32 s28, s28, 0x2c00
	v_lshl_add_u64 v[6:7], s[28:29], 0, v[4:5]
	global_load_dwordx4 v[28:31], v[6:7], off
	s_add_u32 s28, s28, 0x2c00
	v_lshl_add_u64 v[8:9], s[28:29], 0, v[4:5]
	global_load_dwordx4 v[32:35], v[8:9], off
	s_add_u32 s28, s28, 0x2c00
	v_lshl_add_u64 v[6:7], s[28:29], 0, v[4:5]
	global_load_dwordx4 v[36:39], v[6:7], off
	s_add_u32 s28, s28, 0x2c00
	v_lshl_add_u64 v[8:9], s[28:29], 0, v[4:5]
	global_load_dwordx4 v[40:43], v[8:9], off
	s_add_u32 s28, s28, 0x2c00
	v_lshl_add_u64 v[6:7], s[28:29], 0, v[4:5]
	global_load_dwordx4 v[44:47], v[6:7], off
	s_add_u32 s28, s28, 0x2c00
	v_lshl_add_u64 v[8:9], s[28:29], 0, v[4:5]
	global_load_dwordx4 v[48:51], v[8:9], off
	s_add_u32 s28, s28, 0x2c00
	v_lshl_add_u64 v[6:7], s[28:29], 0, v[4:5]
	global_load_dwordx4 v[52:55], v[6:7], off
	s_add_u32 s28, s28, 0x2c00
	v_lshl_add_u64 v[8:9], s[28:29], 0, v[4:5]
	global_load_dwordx4 v[56:59], v[8:9], off
	s_add_u32 s28, s28, 0x2c00
	v_lshl_add_u64 v[6:7], s[28:29], 0, v[4:5]
	global_load_dwordx4 v[60:63], v[6:7], off
	s_add_u32 s28, s28, 0x2c00
	v_lshl_add_u64 v[8:9], s[28:29], 0, v[4:5]
	global_load_dwordx4 v[64:67], v[8:9], off
	s_add_u32 s28, s28, 0x2c00
	v_lshl_add_u64 v[6:7], s[28:29], 0, v[4:5]
	global_load_dwordx4 v[68:71], v[6:7], off
	s_add_u32 s28, s28, 0x2c00
	v_lshl_add_u64 v[8:9], s[28:29], 0, v[4:5]
	global_load_dwordx4 v[72:75], v[8:9], off
	s_add_u32 s28, s28, 0x2c00
	v_lshl_add_u64 v[6:7], s[28:29], 0, v[4:5]
	global_load_dwordx4 v[76:79], v[6:7], off
	s_add_u32 s28, s28, 0x2c00
	v_lshl_add_u64 v[8:9], s[28:29], 0, v[4:5]
	global_load_dwordx4 v[80:83], v[8:9], off
	s_add_u32 s28, s28, 0x2c00
	s_lshl_b32 s26, s14, 19
	s_lshl_b32 s27, s15, 17
	s_add_i32 s26, s26, s27
	s_lshl_b32 s27, s7, 6
	s_add_i32 s26, s26, s27
	s_add_u32 s30, s12, s26
	s_addc_u32 s31, s13, 0
	s_waitcnt vmcnt(0)
	v_cvt_pk_bf16_f32 v84, v20, v24
	v_cvt_pk_bf16_f32 v85, v28, v32
	v_cvt_pk_bf16_f32 v86, v36, v40
	v_cvt_pk_bf16_f32 v87, v44, v48
	v_cvt_pk_bf16_f32 v88, v52, v56
	v_cvt_pk_bf16_f32 v89, v60, v64
	v_cvt_pk_bf16_f32 v90, v68, v72
	v_cvt_pk_bf16_f32 v91, v76, v80
	v_cvt_pk_bf16_f32 v92, v21, v25
	v_cvt_pk_bf16_f32 v93, v29, v33
	v_cvt_pk_bf16_f32 v94, v37, v41
	v_cvt_pk_bf16_f32 v95, v45, v49
	v_cvt_pk_bf16_f32 v96, v53, v57
	v_cvt_pk_bf16_f32 v97, v61, v65
	v_cvt_pk_bf16_f32 v98, v69, v73
	v_cvt_pk_bf16_f32 v99, v77, v81
	v_cvt_pk_bf16_f32 v100, v22, v26
	v_cvt_pk_bf16_f32 v101, v30, v34
	v_cvt_pk_bf16_f32 v102, v38, v42
	v_cvt_pk_bf16_f32 v103, v46, v50
	v_cvt_pk_bf16_f32 v104, v54, v58
	v_cvt_pk_bf16_f32 v105, v62, v66
	v_cvt_pk_bf16_f32 v106, v70, v74
	v_cvt_pk_bf16_f32 v107, v78, v82
	v_cvt_pk_bf16_f32 v108, v23, v27
	v_cvt_pk_bf16_f32 v109, v31, v35
	v_cvt_pk_bf16_f32 v110, v39, v43
	v_cvt_pk_bf16_f32 v111, v47, v51
	v_cvt_pk_bf16_f32 v112, v55, v59
	v_cvt_pk_bf16_f32 v113, v63, v67
	v_cvt_pk_bf16_f32 v114, v71, v75
	v_cvt_pk_bf16_f32 v115, v79, v83
	global_store_dwordx4 v10, v[84:87], s[30:31] offset:-4096
	global_store_dwordx4 v10, v[88:91], s[30:31] offset:-4080
	global_store_dwordx4 v10, v[92:95], s[30:31] offset:-2048
	global_store_dwordx4 v10, v[96:99], s[30:31] offset:-2032
	global_store_dwordx4 v10, v[100:103], s[30:31]
	global_store_dwordx4 v10, v[104:107], s[30:31] offset:16
	global_store_dwordx4 v10, v[108:111], s[30:31] offset:2048
	global_store_dwordx4 v10, v[112:115], s[30:31] offset:2064
	s_addk_i32 s3, 0x680
	s_branch .Lew_loop_a

; __device__ __forceinline__ unsigned pk_bf16(float lo, float hi) { unsigned r; asm volatile("v_cvt_pk_bf16_f32 %0, %1, %2" : "=v"(r) : "v"(lo), "v"(hi)); return r; }
; #define WT_LOAD() do { _Pragma("unroll") for (int i = 0; i < 16; ++i) rg[i] = sp ? sp[(size_t)(k0 + kq + i * 8) * ld] : 0.f; } while (0)
; __device__ __forceinline__ void phase_weights(int wv, const Params& p, int l, LAS unsigned char* lds, int first, int stride) {
;     ...
;     if (ti < 1536) { WT_DECODE(ti); WT_LOAD(); }
;     while (ti < 1536) {
;         bf16_t* cdst = dst + (size_t)n0 * K + k0; const int cK = K;
;         __syncthreads();
; #pragma unroll
;         for (int i = 0; i < 16; ++i) tile[(kq + i * 8) * 65 + nl] = rg[i];
;         ti += stride;
;         if (ti < 1536) { WT_DECODE(ti); WT_LOAD(); }
;         __syncthreads();
;         { const int nn = tid >> 3, ks = tid & 7; float v[16];
; #pragma unroll
;             for (int j = 0; j < 16; ++j) v[j] = tile[(ks * 16 + j) * 65 + nn];
;             u32x4 w0, w1; w0.x = pk_bf16(v[0], v[1]); w0.y = pk_bf16(v[2], v[3]); w0.z = pk_bf16(v[4], v[5]); w0.w = pk_bf16(v[6], v[7]);
;             w1.x = pk_bf16(v[8], v[9]); w1.y = pk_bf16(v[10], v[11]); w1.z = pk_bf16(v[12], v[13]); w1.w = pk_bf16(v[14], v[15]);
;             bf16_t* o = cdst + (size_t)nn * cK + ks * 16; *(u32x4*)o = w0; *(u32x4*)(o + 8) = w1; }
.LBB0_1505:
	s_cmpk_lt_u32 s96, 160
	s_cbranch_scc1 .Lew_end_b
	s_cmpk_lg_u32 s44, 0x100
	s_cbranch_scc1 .Lew_end_b
	s_load_dwordx2 s[8:9], s[90:91], 0x88
	s_load_dwordx2 s[10:11], s[90:91], 0x90
	s_load_dwordx2 s[12:13], s[90:91], 0xa8
	v_readlane_b32 s24, v255, 7
	v_mbcnt_lo_u32_b32 v2, -1, 0
	v_mbcnt_hi_u32_b32 v2, -1, v2
	v_and_b32_e32 v3, 15, v2
	v_lshrrev_b32_e32 v6, 5, v2
	v_lshlrev_b32_e32 v7, 4, v3
	v_mul_u32_u24_e32 v8, 0x2c000, v6
	v_add_u32_e32 v12, v7, v8
	v_add_u32_e32 v12, 0xb00000, v12
	v_mov_b32_e32 v13, 0
	v_and_b32_e32 v8, 16, v2
	v_cmp_ne_u32_e32 vcc, 0, v8
	s_waitcnt lgkmcnt(0)
	v_mov_b32_e32 v4, s8
	v_mov_b32_e32 v5, s9
	v_mov_b32_e32 v8, s10
	v_mov_b32_e32 v9, s11
	s_nop 1
	v_cndmask_b32_e32 v4, v4, v8, vcc
	v_cndmask_b32_e32 v5, v5, v9, vcc
	v_lshl_add_u64 v[4:5], v[4:5], 0, v[12:13]
	v_and_b32_e32 v8, 1, v3
	v_lshlrev_b32_e32 v10, 7, v8
	v_bfe_u32 v8, v3, 1, 2
	v_lshl_add_u32 v10, v8, 2, v10
	v_lshrrev_b32_e32 v8, 3, v3
	v_lshl_add_u32 v10, v8, 5, v10
	v_bfe_u32 v8, v2, 4, 1
	v_lshl_add_u32 v10, v8, 4, v10
	v_add_u32_e32 v10, 2, v10
	v_lshlrev_b32_e32 v10, 11, v10
	v_lshl_add_u32 v10, v6, 5, v10
	s_add_u32 s12, s12, 0xb34c000
	s_addc_u32 s13, s13, 0
	s_lshr_b32 s24, s24, 6
	s_sub_i32 s3, s96, 160
	s_lshl_b32 s3, s3, 3
	s_add_i32 s3, s3, s24
.Lew_loop_b:
	s_cmpk_gt_u32 s3, 0x57f
	s_cbranch_scc1 .Lew_end_b
	s_lshr_b32 s6, s3, 5
	s_and_b32 s7, s3, 31
	s_lshr_b32 s14, s6, 1
	s_and_b32 s15, s6, 1
	s_lshl_b32 s26, s14, 9
	s_lshl_b32 s27, s15, 8
	s_add_i32 s26, s26, s27
	s_mul_i32 s27, s7, 0x58000
	s_add_i32 s28, s26, s27
	s_mov_b32 s29, 0
	v_lshl_add_u64 v[6:7], s[28:29], 0, v[4:5]
	global_load_dwordx4 v[20:23], v[6:7], off
	s_add_u32 s28, s28, 0x2c00
	v_lshl_add_u64 v[8:9], s[28:29], 0, v[4:5]
	global_load_dwordx4 v[24:27], v[8:9], off
	s_add_u32 s28, s28, 0x2c00
	v_lshl_add_u64 v[6:7], s[28:29], 0, v[4:5]
	global_load_dwordx4 v[28:31], v[6:7], off
	s_add_u32 s28, s28, 0x2c00
	v_lshl_add_u64 v[8:9], s[28:29], 0, v[4:5]
	global_load_dwordx4 v[32:35], v[8:9], off
	s_add_u32 s28, s28, 0x2c00
	v_lshl_add_u64 v[6:7], s[28:29], 0, v[4:5]
	global_load_dwordx4 v[36:39], v[6:7], off
	s_add_u32 s28, s28, 0x2c00
	v_lshl_add_u64 v[8:9], s[28:29], 0, v[4:5]
	global_load_dwordx4 v[40:43], v[8:9], off
	s_add_u32 s28, s28, 0x2c00
	v_lshl_add_u64 v[6:7], s[28:29], 0, v[4:5]
	global_load_dwordx4 v[44:47], v[6:7], off
	s_add_u32 s28, s28, 0x2c00
	v_lshl_add_u64 v[8:9], s[28:29], 0, v[4:5]
	global_load_dwordx4 v[48:51], v[8:9], off
	s_add_u32 s28, s28, 0x2c00
	v_lshl_add_u64 v[6:7], s[28:29], 0, v[4:5]
	global_load_dwordx4 v[52:55], v[6:7], off
	s_add_u32 s28, s28, 0x2c00
	v_lshl_add_u64 v[8:9], s[28:29], 0, v[4:5]
	global_load_dwordx4 v[56:59], v[8:9], off
	s_add_u32 s28, s28, 0x2c00
	v_lshl_add_u64 v[6:7], s[28:29], 0, v[4:5]
	global_load_dwordx4 v[60:63], v[6:7], off
	s_add_u32 s28, s28, 0x2c00
	v_lshl_add_u64 v[8:9], s[28:29], 0, v[4:5]
	global_load_dwordx4 v[64:67], v[8:9], off
	s_add_u32 s28, s28, 0x2c00
	v_lshl_add_u64 v[6:7], s[28:29], 0, v[4:5]
	global_load_dwordx4 v[68:71], v[6:7], off
	s_add_u32 s28, s28, 0x2c00
	v_lshl_add_u64 v[8:9], s[28:29], 0, v[4:5]
	global_load_dwordx4 v[72:75], v[8:9], off
	s_add_u32 s28, s28, 0x2c00
	v_lshl_add_u64 v[6:7], s[28:29], 0, v[4:5]
	global_load_dwordx4 v[76:79], v[6:7], off
	s_add_u32 s28, s28, 0x2c00
	v_lshl_add_u64 v[8:9], s[28:29], 0, v[4:5]
	global_load_dwordx4 v[80:83], v[8:9], off
	s_add_u32 s28, s28, 0x2c00
	s_lshl_b32 s26, s14, 19
	s_lshl_b32 s27, s15, 17
	s_add_i32 s26, s26, s27
	s_lshl_b32 s27, s7, 6
	s_add_i32 s26, s26, s27
	s_add_u32 s30, s12, s26
	s_addc_u32 s31, s13, 0
	s_waitcnt vmcnt(0)
	v_cvt_pk_bf16_f32 v84, v20, v24
	v_cvt_pk_bf16_f32 v85, v28, v32
	v_cvt_pk_bf16_f32 v86, v36, v40
	v_cvt_pk_bf16_f32 v87, v44, v48
	v_cvt_pk_bf16_f32 v88, v52, v56
	v_cvt_pk_bf16_f32 v89, v60, v64
	v_cvt_pk_bf16_f32 v90, v68, v72
	v_cvt_pk_bf16_f32 v91, v76, v80
	v_cvt_pk_bf16_f32 v92, v21, v25
	v_cvt_pk_bf16_f32 v93, v29, v33
	v_cvt_pk_bf16_f32 v94, v37, v41
	v_cvt_pk_bf16_f32 v95, v45, v49
	v_cvt_pk_bf16_f32 v96, v53, v57
	v_cvt_pk_bf16_f32 v97, v61, v65
	v_cvt_pk_bf16_f32 v98, v69, v73
	v_cvt_pk_bf16_f32 v99, v77, v81
	v_cvt_pk_bf16_f32 v100, v22, v26
	v_cvt_pk_bf16_f32 v101, v30, v34
	v_cvt_pk_bf16_f32 v102, v38, v42
	v_cvt_pk_bf16_f32 v103, v46, v50
	v_cvt_pk_bf16_f32 v104, v54, v58
	v_cvt_pk_bf16_f32 v105, v62, v66
	v_cvt_pk_bf16_f32 v106, v70, v74
	v_cvt_pk_bf16_f32 v107, v78, v82
	v_cvt_pk_bf16_f32 v108, v23, v27
	v_cvt_pk_bf16_f32 v109, v31, v35
	v_cvt_pk_bf16_f32 v110, v39, v43
	v_cvt_pk_bf16_f32 v111, v47, v51
	v_cvt_pk_bf16_f32 v112, v55, v59
	v_cvt_pk_bf16_f32 v113, v63, v67
	v_cvt_pk_bf16_f32 v114, v71, v75
	v_cvt_pk_bf16_f32 v115, v79, v83
	global_store_dwordx4 v10, v[84:87], s[30:31] offset:-4096
	global_store_dwordx4 v10, v[88:91], s[30:31] offset:-4080
	global_store_dwordx4 v10, v[92:95], s[30:31] offset:-2048
	global_store_dwordx4 v10, v[96:99], s[30:31] offset:-2032
	global_store_dwordx4 v10, v[100:103], s[30:31]
	global_store_dwordx4 v10, v[104:107], s[30:31] offset:16
	global_store_dwordx4 v10, v[108:111], s[30:31] offset:2048
	global_store_dwordx4 v10, v[112:115], s[30:31] offset:2064
	s_addk_i32 s3, 0x300
	s_branch .Lew_loop_b
